# pass C tail window: waves 4..7 (which finish pass C before the sample-first waves 0..3) each convert one deferred w_out_c item before the workgroup arrives at the barrier; that barrier's hook shrinks
# speedup vs baseline: 1.0013x; 1.0013x over previous
.Ltr_b4:
	s_cmp_eq_u32 s98, 7
	s_cbranch_scc1 .Lb7_ret
	s_cmp_eq_u32 s98, 8
	s_cbranch_scc1 .Lb8_ret
	s_cmp_eq_u32 s98, 10
	s_cbranch_scc1 .Lpc_tail_ret
	s_branch .Lpc_back2

.Lpc_nofin:
	s_addk_i32 s46, 0x100
	s_cmpk_lt_i32 s46, 0x400
	s_cbranch_scc1 .Lpc_item
	v_readlane_b32 s6, v255, 7
	v_readlane_b32 s7, v255, 2
	s_nop 0
	s_lshr_b32 s7, s7, 6
	s_cmp_lt_u32 s7, 4
	s_cbranch_scc1 .Lpc_tail_done
	s_mov_b64 exec, -1
	s_mov_b64 s[100:101], s[4:5]
	s_mov_b32 s98, 10
	s_mov_b32 s99, 0x47ff
	s_movk_i32 s48, 0x1000
	s_add_i32 s92, s7, 6
	s_lshl_b32 s92, s92, 8
	s_add_i32 s92, s92, s6
	s_add_i32 s92, s92, 0x3800
	v_readlane_b32 s0, v255, 3
	v_readlane_b32 s1, v255, 4
	v_readlane_b32 s2, v255, 0
	v_readlane_b32 s3, v255, 1
	v_mov_b32_e32 v163, v0
	v_and_b32_e32 v162, 63, v0
	s_add_i32 s7, s7, -4
	s_lshl_b32 s30, s7, 14
	s_cmp_lt_u32 s7, 2
	s_cbranch_scc1 .Lpc_tail_go
	s_mul_i32 s30, s7, 0x2100
	s_add_i32 s30, s30, 0x13f00
.Lpc_tail_go:
	s_nop 4
	s_branch .Ltr_f4
.Lpc_tail_ret:
	s_mov_b32 s98, 0
	s_mov_b64 s[4:5], s[100:101]
	s_mov_b64 exec, -1
	v_mbcnt_lo_u32_b32 v1, -1, 0
.Lpc_tail_done:
	s_branch .LBB0_1414
.Lpc_compiled:
	s_load_dwordx4 s[28:31], s[2:3], 0xc8
	s_load_dwordx2 s[0:1], s[2:3], 0xa0
	v_and_b32_e32 v3, 63, v2
	v_lshlrev_b32_e32 v96, 4, v3
	v_and_b32_e32 v94, 31, v2
	s_waitcnt lgkmcnt(0)
	s_add_u32 s2, s30, 0x5200000
	s_addc_u32 s3, s31, 0
	s_add_u32 s40, s30, 0x600000
	s_addc_u32 s41, s31, 0
	s_ashr_i32 s42, s6, 6
	v_cmp_lt_u32_e64 s[6:7], 31, v3
	v_mbcnt_hi_u32_b32 v3, -1, v1
	s_add_u32 s26, s30, 0x30000
	v_and_b32_e32 v10, 64, v3
	s_addc_u32 s27, s31, 0
	s_lshl_b32 s8, s42, 13
	v_xor_b32_e32 v9, 32, v3
	v_add_u32_e32 v10, 64, v10
	s_add_i32 s33, s8, 0
	v_cmp_lt_i32_e32 vcc, v9, v10
	v_and_b32_e32 v6, 3, v2
	v_lshrrev_b32_e32 v7, 2, v2
	v_bfe_u32 v8, v2, 5, 1
	v_mov_b32_e32 v97, 0
	v_cndmask_b32_e32 v3, v3, v9, vcc
	v_lshl_add_u32 v206, v94, 6, s33
	s_movk_i32 s10, 0xffc4
	v_bfe_u32 v104, v2, 1, 5
	v_lshlrev_b32_e32 v2, 3, v2
	v_lshl_add_u64 v[4:5], s[30:31], 0, v[96:97]
	s_mov_b64 s[8:9], 0x140000
	v_lshlrev_b32_e32 v167, 2, v3
	v_mad_i32_i24 v9, v94, s10, v206
	v_and_or_b32 v3, v7, 4, v6
	s_mov_b64 s[10:11], 0x1c0000
	v_and_b32_e32 v2, 8, v2
	v_lshl_add_u64 v[98:99], v[4:5], 0, s[8:9]
	v_lshlrev_b32_e32 v6, 3, v3
	v_lshl_add_u64 v[102:103], v[4:5], 0, s[10:11]
	v_lshlrev_b32_e32 v3, 6, v104
	v_lshlrev_b32_e32 v5, 2, v2
	v_lshlrev_b32_e32 v96, 1, v2
	v_lshlrev_b32_e32 v100, 3, v8
	v_add3_u32 v207, s33, v3, v5
	v_lshl_add_u64 v[2:3], s[30:31], 0, v[96:97]
	s_mov_b64 s[10:11], 0xd600000
	v_lshl_add_u64 v[106:107], v[2:3], 0, s[10:11]
	v_or_b32_e32 v2, 2, v100
	v_cmp_eq_u32_e64 s[12:13], v2, v94
	v_or_b32_e32 v2, 4, v100
	v_or_b32_e32 v3, 1, v100
	v_cmp_eq_u32_e64 s[16:17], v2, v94
	v_or_b32_e32 v2, 6, v100
	v_cmp_eq_u32_e64 s[14:15], v3, v94
	v_or_b32_e32 v3, 3, v100
	v_cmp_eq_u32_e64 s[20:21], v2, v94
	v_or_b32_e32 v2, 7, v100
	v_cmp_eq_u32_e64 s[18:19], v3, v94
	v_or_b32_e32 v3, 5, v100
	v_cmp_eq_u32_e64 s[24:25], v2, v94
	v_and_or_b32 v2, v7, 3, v100
	v_lshlrev_b32_e32 v96, 2, v94
	v_cmp_eq_u32_e64 s[22:23], v3, v94
	v_lshl_add_u32 v5, v2, 6, s33
	v_lshl_add_u64 v[2:3], s[28:29], 0, v[96:97]
	s_mov_b64 s[28:29], 0x6084000
	v_lshlrev_b32_e32 v4, 8, v8
	v_lshl_add_u64 v[114:115], v[2:3], 0, s[28:29]
	s_mov_b64 s[28:29], 0x6094000
	s_mov_b32 s43, 0
	v_lshlrev_b32_e32 v101, 1, v94
	v_mov_b32_e32 v95, v97
	v_cmp_gt_u32_e64 s[8:9], 16, v94
	v_cmp_eq_u32_e64 s[10:11], v100, v94
	v_mov_b32_e32 v105, v97
	v_or_b32_e32 v108, 32, v104
	v_mov_b32_e32 v109, v97
	v_or_b32_e32 v110, 64, v104
	v_mov_b32_e32 v111, v97
	v_or_b32_e32 v112, 0x60, v104
	v_mov_b32_e32 v113, v97
	v_lshl_add_u64 v[116:117], v[2:3], 0, s[28:29]
	v_lshlrev_b32_e32 v96, 1, v100
	s_mov_b32 s44, 0x5040100
	s_mov_b32 s45, 0x20000
	s_mov_b32 s46, 0x40000
	s_mov_b32 s47, 0x60000
	s_xor_b64 s[28:29], s[6:7], -1
	v_add_u32_e32 v208, v5, v6
	v_add_u32_e32 v209, v9, v4
	v_readlane_b32 s48, v255, 7
	s_branch .LBB0_1389

.LBB0_1414:
	s_waitcnt vmcnt(0)
	s_barrier
	s_cmp_eq_u32 s97, 0x100
	s_cbranch_scc0 .Lb8_skip
	v_readlane_b32 s7, v255, 2
	v_readlane_b32 s6, v255, 7
	s_nop 0
	s_lshr_b32 s7, s7, 6
	s_cmp_eq_u32 s7, 0
	s_cbranch_scc1 .Lb8_skip
	s_cmp_gt_u32 s7, 2
	s_cbranch_scc1 .Lb8_skip
	s_mov_b64 s[46:47], exec
	s_mov_b64 exec, -1
	s_add_i32 s92, s7, 13
	s_lshl_b32 s92, s92, 8
	s_add_i32 s92, s92, s6
	s_add_i32 s92, s92, 0x3800
	s_mov_b64 s[100:101], s[4:5]
	s_mov_b32 s98, 8
	s_mov_b32 s99, 0x47ff
	s_movk_i32 s48, 0x1000
	v_readlane_b32 s0, v255, 3
	v_readlane_b32 s1, v255, 4
	v_readlane_b32 s2, v255, 0
	v_readlane_b32 s3, v255, 1
	v_mov_b32_e32 v163, v0
	v_and_b32_e32 v162, 63, v0
	s_lshl_b32 s30, s7, 14
	s_nop 4
	s_branch .Ltr_f4
